# weight conversion: 16 tile-row addresses from one 64-bit multiply plus a chain of 64-bit adds instead of 16 multiplies (4 sites)
# baseline (speedup 1.0000x reference)
; __device__ __forceinline__ void p0_item(const float* W, const float* gain, int K, int N, bf16_t* WT, int mode, LAS float* scr, int item, int lane) {
;     const int nblk = N / 64, kb = item / nblk, nb = item % nblk, k0 = 64 * kb, n0 = 64 * nb;
;     const int kr = lane >> 4, nc = (lane & 15) * 4;
;     f32x4 v[16];
; #pragma unroll
;     for (int i = 0; i < 16; ++i) v[i] = __builtin_nontemporal_load((const f32x4*)(W + (size_t)(k0 + 4 * i + kr) * N + n0 + nc));
;     if (gain) {
; #pragma unroll
;         for (int i = 0; i < 16; ++i) v[i] = v[i] * gain[k0 + 4 * i + kr];
.LBB0_114:
	s_or_b64 exec, exec, s[8:9]
	v_lshrrev_b32_e32 v5, 6, v58
	v_cvt_f32_u32_e32 v6, v5
	v_sub_u32_e32 v9, 0, v5
	v_sub_u32_e32 v8, 0, v4
	v_max_i32_e32 v8, v4, v8
	v_rcp_iflag_f32_e32 v6, v6
	v_ashrrev_i32_e32 v7, 31, v4
	v_mul_f32_e32 v6, 0x4f7ffffe, v6
	v_cvt_u32_f32_e32 v6, v6
	v_mul_lo_u32 v9, v9, v6
	v_mul_hi_u32 v9, v6, v9
	v_add_u32_e32 v6, v6, v9
	v_mul_hi_u32 v6, v8, v6
	v_mul_lo_u32 v9, v6, v5
	v_sub_u32_e32 v8, v8, v9
	v_add_u32_e32 v10, 1, v6
	v_cmp_ge_u32_e32 vcc, v8, v5
	v_sub_u32_e32 v9, v8, v5
	s_nop 0
	v_cndmask_b32_e32 v6, v6, v10, vcc
	v_cndmask_b32_e32 v8, v8, v9, vcc
	v_add_u32_e32 v9, 1, v6
	v_cmp_ge_u32_e32 vcc, v8, v5
	s_nop 1
	v_cndmask_b32_e32 v6, v6, v9, vcc
	v_xor_b32_e32 v6, v6, v7
	v_sub_u32_e32 v6, v6, v7
	v_mul_lo_u32 v5, v6, v5
	v_sub_u32_e32 v73, v4, v5
	v_lshlrev_b32_e32 v72, 6, v6
	v_lshlrev_b32_e32 v74, 6, v73
	v_or_b32_e32 v78, v72, v81
	v_ashrrev_i32_e32 v75, 31, v74
	v_lshl_add_u64 v[2:3], v[74:75], 2, v[2:3]
	v_ashrrev_i32_e32 v79, 31, v78
	v_lshl_add_u64 v[60:61], v[2:3], 0, v[0:1]
	v_mul_lo_u32 v64, v79, v58
	v_mad_u64_u32 v[2:3], s[8:9], v78, v58, 0
	v_lshlrev_b32_e32 v124, 4, v58
	v_mov_b32_e32 v125, 0
	v_add_u32_e32 v3, v3, v64
	v_lshl_add_u64 v[2:3], v[2:3], 2, v[60:61]
	v_lshl_add_u64 v[4:5], v[2:3], 0, v[124:125]
	v_lshl_add_u64 v[10:11], v[4:5], 0, v[124:125]
	v_lshl_add_u64 v[12:13], v[10:11], 0, v[124:125]
	v_lshl_add_u64 v[18:19], v[12:13], 0, v[124:125]
	v_lshl_add_u64 v[20:21], v[18:19], 0, v[124:125]
	v_lshl_add_u64 v[26:27], v[20:21], 0, v[124:125]
	v_lshl_add_u64 v[28:29], v[26:27], 0, v[124:125]
	v_lshl_add_u64 v[34:35], v[28:29], 0, v[124:125]
	v_lshl_add_u64 v[36:37], v[34:35], 0, v[124:125]
	v_lshl_add_u64 v[42:43], v[36:37], 0, v[124:125]
	v_lshl_add_u64 v[44:45], v[42:43], 0, v[124:125]
	v_lshl_add_u64 v[50:51], v[44:45], 0, v[124:125]
	v_lshl_add_u64 v[52:53], v[50:51], 0, v[124:125]
	v_lshl_add_u64 v[62:63], v[52:53], 0, v[124:125]
	v_lshl_add_u64 v[58:59], v[62:63], 0, v[124:125]
	global_load_dwordx4 v[6:9], v[2:3], off nt
	s_nop 0
	global_load_dwordx4 v[2:5], v[4:5], off nt
	s_nop 0
	global_load_dwordx4 v[14:17], v[10:11], off nt
	s_nop 0
	global_load_dwordx4 v[10:13], v[12:13], off nt
	s_nop 0
	global_load_dwordx4 v[22:25], v[18:19], off nt
	s_nop 0
	global_load_dwordx4 v[18:21], v[20:21], off nt
	s_nop 0
	global_load_dwordx4 v[30:33], v[26:27], off nt
	s_nop 0
	global_load_dwordx4 v[26:29], v[28:29], off nt
	s_nop 0
	global_load_dwordx4 v[38:41], v[34:35], off nt
	s_nop 0
	global_load_dwordx4 v[34:37], v[36:37], off nt
	s_nop 0
	global_load_dwordx4 v[46:49], v[42:43], off nt
	s_nop 0
	global_load_dwordx4 v[42:45], v[44:45], off nt
	s_nop 0
	global_load_dwordx4 v[54:57], v[50:51], off nt
	s_nop 0
	global_load_dwordx4 v[50:53], v[52:53], off nt
	s_nop 0
	global_load_dwordx4 v[62:65], v[62:63], off nt
	s_nop 0
	global_load_dwordx4 v[58:61], v[58:59], off nt
	v_cmp_ne_u64_e32 vcc, 0, v[76:77]
	s_and_saveexec_b64 s[8:9], vcc
	s_cbranch_execz .LBB0_105
	v_lshl_add_u64 v[76:77], v[78:79], 2, v[76:77]
	global_load_dword v94, v[76:77], off
	global_load_dword v96, v[76:77], off offset:16
	global_load_dword v98, v[76:77], off offset:32
	global_load_dword v100, v[76:77], off offset:48
	global_load_dword v102, v[76:77], off offset:64
	global_load_dword v104, v[76:77], off offset:80
	global_load_dword v106, v[76:77], off offset:96
	global_load_dword v108, v[76:77], off offset:112
	global_load_dword v110, v[76:77], off offset:128
	global_load_dword v112, v[76:77], off offset:144
	global_load_dword v114, v[76:77], off offset:160
	global_load_dword v116, v[76:77], off offset:176
	global_load_dword v118, v[76:77], off offset:192
	global_load_dword v120, v[76:77], off offset:208
	global_load_dword v122, v[76:77], off offset:224
	s_nop 0
	global_load_dword v76, v[76:77], off offset:240
	s_waitcnt vmcnt(15)
	v_pk_mul_f32 v[8:9], v[8:9], v[94:95] op_sel_hi:[1,0]
	v_pk_mul_f32 v[6:7], v[6:7], v[94:95] op_sel_hi:[1,0]
	s_waitcnt vmcnt(14)
	v_pk_mul_f32 v[4:5], v[4:5], v[96:97] op_sel_hi:[1,0]
	v_pk_mul_f32 v[2:3], v[2:3], v[96:97] op_sel_hi:[1,0]
	s_waitcnt vmcnt(13)
	v_pk_mul_f32 v[16:17], v[16:17], v[98:99] op_sel_hi:[1,0]
	v_pk_mul_f32 v[14:15], v[14:15], v[98:99] op_sel_hi:[1,0]
	s_waitcnt vmcnt(12)
	v_pk_mul_f32 v[12:13], v[12:13], v[100:101] op_sel_hi:[1,0]
	v_pk_mul_f32 v[10:11], v[10:11], v[100:101] op_sel_hi:[1,0]
	s_waitcnt vmcnt(11)
	v_pk_mul_f32 v[24:25], v[24:25], v[102:103] op_sel_hi:[1,0]
	v_pk_mul_f32 v[22:23], v[22:23], v[102:103] op_sel_hi:[1,0]
	s_waitcnt vmcnt(10)
	v_pk_mul_f32 v[20:21], v[20:21], v[104:105] op_sel_hi:[1,0]
	v_pk_mul_f32 v[18:19], v[18:19], v[104:105] op_sel_hi:[1,0]
	s_waitcnt vmcnt(9)
	v_pk_mul_f32 v[32:33], v[32:33], v[106:107] op_sel_hi:[1,0]
	v_pk_mul_f32 v[30:31], v[30:31], v[106:107] op_sel_hi:[1,0]
	s_waitcnt vmcnt(8)
	v_pk_mul_f32 v[28:29], v[28:29], v[108:109] op_sel_hi:[1,0]
	v_pk_mul_f32 v[26:27], v[26:27], v[108:109] op_sel_hi:[1,0]
	s_waitcnt vmcnt(7)
	v_pk_mul_f32 v[40:41], v[40:41], v[110:111] op_sel_hi:[1,0]
	v_pk_mul_f32 v[38:39], v[38:39], v[110:111] op_sel_hi:[1,0]
	s_waitcnt vmcnt(6)
	v_pk_mul_f32 v[36:37], v[36:37], v[112:113] op_sel_hi:[1,0]
	v_pk_mul_f32 v[34:35], v[34:35], v[112:113] op_sel_hi:[1,0]
	s_waitcnt vmcnt(5)
	v_pk_mul_f32 v[48:49], v[48:49], v[114:115] op_sel_hi:[1,0]
	v_pk_mul_f32 v[46:47], v[46:47], v[114:115] op_sel_hi:[1,0]
	s_waitcnt vmcnt(4)
	v_pk_mul_f32 v[44:45], v[44:45], v[116:117] op_sel_hi:[1,0]
	v_pk_mul_f32 v[42:43], v[42:43], v[116:117] op_sel_hi:[1,0]
	s_waitcnt vmcnt(3)
	v_pk_mul_f32 v[56:57], v[56:57], v[118:119] op_sel_hi:[1,0]
	v_pk_mul_f32 v[54:55], v[54:55], v[118:119] op_sel_hi:[1,0]
	s_waitcnt vmcnt(2)
	v_pk_mul_f32 v[52:53], v[52:53], v[120:121] op_sel_hi:[1,0]
	v_pk_mul_f32 v[50:51], v[50:51], v[120:121] op_sel_hi:[1,0]
	s_waitcnt vmcnt(1)
	v_pk_mul_f32 v[64:65], v[64:65], v[122:123] op_sel_hi:[1,0]
	v_pk_mul_f32 v[62:63], v[62:63], v[122:123] op_sel_hi:[1,0]
	s_waitcnt vmcnt(0)
	v_pk_mul_f32 v[60:61], v[60:61], v[76:77] op_sel_hi:[1,0]
	v_pk_mul_f32 v[58:59], v[58:59], v[76:77] op_sel_hi:[1,0]
	s_branch .LBB0_105

; __device__ __forceinline__ void p0_item(const float* W, const float* gain, int K, int N, bf16_t* WT, int mode, LAS float* scr, int item, int lane) {
;     const int nblk = N / 64, kb = item / nblk, nb = item % nblk, k0 = 64 * kb, n0 = 64 * nb;
;     const int kr = lane >> 4, nc = (lane & 15) * 4;
;     f32x4 v[16];
; #pragma unroll
;     for (int i = 0; i < 16; ++i) v[i] = __builtin_nontemporal_load((const f32x4*)(W + (size_t)(k0 + 4 * i + kr) * N + n0 + nc));
;     if (gain) {
; #pragma unroll
;         for (int i = 0; i < 16; ++i) v[i] = v[i] * gain[k0 + 4 * i + kr];
.LBB0_353:
	s_or_b64 exec, exec, s[0:1]
	v_lshrrev_b32_e32 v5, 6, v58
	v_cvt_f32_u32_e32 v6, v5
	v_sub_u32_e32 v9, 0, v5
	v_sub_u32_e32 v8, 0, v4
	v_max_i32_e32 v8, v4, v8
	v_rcp_iflag_f32_e32 v6, v6
	v_ashrrev_i32_e32 v7, 31, v4
	v_mul_f32_e32 v6, 0x4f7ffffe, v6
	v_cvt_u32_f32_e32 v6, v6
	v_mul_lo_u32 v9, v9, v6
	v_mul_hi_u32 v9, v6, v9
	v_add_u32_e32 v6, v6, v9
	v_mul_hi_u32 v6, v8, v6
	v_mul_lo_u32 v9, v6, v5
	v_sub_u32_e32 v8, v8, v9
	v_add_u32_e32 v10, 1, v6
	v_cmp_ge_u32_e64 s[0:1], v8, v5
	v_sub_u32_e32 v9, v8, v5
	s_nop 0
	v_cndmask_b32_e64 v6, v6, v10, s[0:1]
	v_cndmask_b32_e64 v8, v8, v9, s[0:1]
	v_add_u32_e32 v9, 1, v6
	v_cmp_ge_u32_e64 s[0:1], v8, v5
	s_nop 1
	v_cndmask_b32_e64 v6, v6, v9, s[0:1]
	v_xor_b32_e32 v6, v6, v7
	v_sub_u32_e32 v6, v6, v7
	v_mul_lo_u32 v5, v6, v5
	v_sub_u32_e32 v75, v4, v5
	v_lshlrev_b32_e32 v74, 6, v6
	v_lshlrev_b32_e32 v76, 6, v75
	v_or_b32_e32 v78, v74, v81
	v_ashrrev_i32_e32 v77, 31, v76
	v_lshl_add_u64 v[2:3], v[76:77], 2, v[2:3]
	v_ashrrev_i32_e32 v79, 31, v78
	v_lshl_add_u64 v[60:61], v[2:3], 0, v[0:1]
	v_mul_lo_u32 v64, v79, v58
	v_mad_u64_u32 v[2:3], s[0:1], v78, v58, 0
	v_lshlrev_b32_e32 v124, 4, v58
	v_mov_b32_e32 v125, 0
	v_add_u32_e32 v3, v3, v64
	v_lshl_add_u64 v[2:3], v[2:3], 2, v[60:61]
	v_lshl_add_u64 v[4:5], v[2:3], 0, v[124:125]
	v_lshl_add_u64 v[10:11], v[4:5], 0, v[124:125]
	v_lshl_add_u64 v[12:13], v[10:11], 0, v[124:125]
	v_lshl_add_u64 v[18:19], v[12:13], 0, v[124:125]
	v_lshl_add_u64 v[20:21], v[18:19], 0, v[124:125]
	v_lshl_add_u64 v[26:27], v[20:21], 0, v[124:125]
	v_lshl_add_u64 v[28:29], v[26:27], 0, v[124:125]
	v_lshl_add_u64 v[34:35], v[28:29], 0, v[124:125]
	v_lshl_add_u64 v[36:37], v[34:35], 0, v[124:125]
	v_lshl_add_u64 v[42:43], v[36:37], 0, v[124:125]
	v_lshl_add_u64 v[44:45], v[42:43], 0, v[124:125]
	v_lshl_add_u64 v[50:51], v[44:45], 0, v[124:125]
	v_lshl_add_u64 v[52:53], v[50:51], 0, v[124:125]
	v_lshl_add_u64 v[62:63], v[52:53], 0, v[124:125]
	v_lshl_add_u64 v[58:59], v[62:63], 0, v[124:125]
	global_load_dwordx4 v[6:9], v[2:3], off nt
	s_nop 0
	global_load_dwordx4 v[2:5], v[4:5], off nt
	s_nop 0
	global_load_dwordx4 v[14:17], v[10:11], off nt
	s_nop 0
	global_load_dwordx4 v[10:13], v[12:13], off nt
	s_nop 0
	global_load_dwordx4 v[22:25], v[18:19], off nt
	s_nop 0
	global_load_dwordx4 v[18:21], v[20:21], off nt
	s_nop 0
	global_load_dwordx4 v[30:33], v[26:27], off nt
	s_nop 0
	global_load_dwordx4 v[26:29], v[28:29], off nt
	s_nop 0
	global_load_dwordx4 v[38:41], v[34:35], off nt
	s_nop 0
	global_load_dwordx4 v[34:37], v[36:37], off nt
	s_nop 0
	global_load_dwordx4 v[46:49], v[42:43], off nt
	s_nop 0
	global_load_dwordx4 v[42:45], v[44:45], off nt
	s_nop 0
	global_load_dwordx4 v[54:57], v[50:51], off nt
	s_nop 0
	global_load_dwordx4 v[50:53], v[52:53], off nt
	s_nop 0
	global_load_dwordx4 v[62:65], v[62:63], off nt
	s_nop 0
	global_load_dwordx4 v[58:61], v[58:59], off nt
	v_cmp_ne_u64_e64 s[0:1], 0, v[72:73]
	s_and_saveexec_b64 s[10:11], s[0:1]
	s_cbranch_execz .LBB0_316
	v_lshl_add_u64 v[72:73], v[78:79], 2, v[72:73]
	global_load_dword v94, v[72:73], off
	global_load_dword v96, v[72:73], off offset:16
	global_load_dword v98, v[72:73], off offset:32
	global_load_dword v100, v[72:73], off offset:48
	global_load_dword v102, v[72:73], off offset:64
	global_load_dword v104, v[72:73], off offset:80
	global_load_dword v106, v[72:73], off offset:96
	global_load_dword v108, v[72:73], off offset:112
	global_load_dword v110, v[72:73], off offset:128
	global_load_dword v112, v[72:73], off offset:144
	global_load_dword v114, v[72:73], off offset:160
	global_load_dword v116, v[72:73], off offset:176
	global_load_dword v118, v[72:73], off offset:192
	global_load_dword v120, v[72:73], off offset:208
	global_load_dword v122, v[72:73], off offset:224
	s_nop 0
	global_load_dword v72, v[72:73], off offset:240
	s_waitcnt vmcnt(15)
	v_pk_mul_f32 v[8:9], v[8:9], v[94:95] op_sel_hi:[1,0]
	v_pk_mul_f32 v[6:7], v[6:7], v[94:95] op_sel_hi:[1,0]
	s_waitcnt vmcnt(14)
	v_pk_mul_f32 v[4:5], v[4:5], v[96:97] op_sel_hi:[1,0]
	v_pk_mul_f32 v[2:3], v[2:3], v[96:97] op_sel_hi:[1,0]
	s_waitcnt vmcnt(13)
	v_pk_mul_f32 v[16:17], v[16:17], v[98:99] op_sel_hi:[1,0]
	v_pk_mul_f32 v[14:15], v[14:15], v[98:99] op_sel_hi:[1,0]
	s_waitcnt vmcnt(12)
	v_pk_mul_f32 v[12:13], v[12:13], v[100:101] op_sel_hi:[1,0]
	v_pk_mul_f32 v[10:11], v[10:11], v[100:101] op_sel_hi:[1,0]
	s_waitcnt vmcnt(11)
	v_pk_mul_f32 v[24:25], v[24:25], v[102:103] op_sel_hi:[1,0]
	v_pk_mul_f32 v[22:23], v[22:23], v[102:103] op_sel_hi:[1,0]
	s_waitcnt vmcnt(10)
	v_pk_mul_f32 v[20:21], v[20:21], v[104:105] op_sel_hi:[1,0]
	v_pk_mul_f32 v[18:19], v[18:19], v[104:105] op_sel_hi:[1,0]
	s_waitcnt vmcnt(9)
	v_pk_mul_f32 v[32:33], v[32:33], v[106:107] op_sel_hi:[1,0]
	v_pk_mul_f32 v[30:31], v[30:31], v[106:107] op_sel_hi:[1,0]
	s_waitcnt vmcnt(8)
	v_pk_mul_f32 v[28:29], v[28:29], v[108:109] op_sel_hi:[1,0]
	v_pk_mul_f32 v[26:27], v[26:27], v[108:109] op_sel_hi:[1,0]
	s_waitcnt vmcnt(7)
	v_pk_mul_f32 v[40:41], v[40:41], v[110:111] op_sel_hi:[1,0]
	v_pk_mul_f32 v[38:39], v[38:39], v[110:111] op_sel_hi:[1,0]
	s_waitcnt vmcnt(6)
	v_pk_mul_f32 v[36:37], v[36:37], v[112:113] op_sel_hi:[1,0]
	v_pk_mul_f32 v[34:35], v[34:35], v[112:113] op_sel_hi:[1,0]
	s_waitcnt vmcnt(5)
	v_pk_mul_f32 v[48:49], v[48:49], v[114:115] op_sel_hi:[1,0]
	v_pk_mul_f32 v[46:47], v[46:47], v[114:115] op_sel_hi:[1,0]
	s_waitcnt vmcnt(4)
	v_pk_mul_f32 v[44:45], v[44:45], v[116:117] op_sel_hi:[1,0]
	v_pk_mul_f32 v[42:43], v[42:43], v[116:117] op_sel_hi:[1,0]
	s_waitcnt vmcnt(3)
	v_pk_mul_f32 v[56:57], v[56:57], v[118:119] op_sel_hi:[1,0]
	v_pk_mul_f32 v[54:55], v[54:55], v[118:119] op_sel_hi:[1,0]
	s_waitcnt vmcnt(2)
	v_pk_mul_f32 v[52:53], v[52:53], v[120:121] op_sel_hi:[1,0]
	v_pk_mul_f32 v[50:51], v[50:51], v[120:121] op_sel_hi:[1,0]
	s_waitcnt vmcnt(1)
	v_pk_mul_f32 v[64:65], v[64:65], v[122:123] op_sel_hi:[1,0]
	v_pk_mul_f32 v[62:63], v[62:63], v[122:123] op_sel_hi:[1,0]
	s_waitcnt vmcnt(0)
	v_pk_mul_f32 v[60:61], v[60:61], v[72:73] op_sel_hi:[1,0]
	v_pk_mul_f32 v[58:59], v[58:59], v[72:73] op_sel_hi:[1,0]
	s_branch .LBB0_316
